# v28 + P0b x0 loop row 0: gain/scale vector loads of column blocks 1..3 issued with block 0's (one wait) instead of a pair-per-block ladder
# speedup vs baseline: 1.0130x; 1.0030x over previous
; __device__ __forceinline__ unsigned pk2(float lo, float hi) { return f2bf(lo) | (f2bf(hi) << 16); }
; __host__ __device__ __forceinline__ unsigned img_off(unsigned row, unsigned col, unsigned KT) { return (((row >> 8) * KT + (col >> 6)) << 14) + (((row >> 7) & 1u) << 13) + hl_off(row & 127u, col & 63u); }
; __device__ __forceinline__ float gain_clamp(float g) { return fabsf(g) < 1e-5f ? copysignf(1e-5f, g) : g; }
; __device__ __forceinline__ void phase_p0b(const Args& a) {
;     ...
;             for (int j = 0; j < 4; ++j) {
;                 const int k0 = 256 * j + 4 * lane;
;                 f32x4 vv = v[u][j];
;                 if (lat) {
; #pragma unroll
;                     for (int e = 0; e < 4; ++e) { const float ang = ((j < 2) ? prow : pcol) * omega[e]; vv[e] += (j & 1) ? __cosf(ang) : __sinf(ang); }
;                 }
;                 q += (vv[0] * vv[0] + vv[1] * vv[1]) + (vv[2] * vv[2] + vv[3] * vv[3]);
;                 const f32x4 gg = *(const f32x4*)(g1 + k0);
;                 const f32x4 sc = *(const f32x4*)(mod + (size_t)bb * NMODC + DM + k0);
;                 f32x4 gc = gg * (1.0f + sc);
; #pragma unroll
;                 for (int e = 0; e < 4; ++e) gc[e] = gain_clamp(gc[e]);
;                 const f32x4 y = vv * gc;
;                 if (okr[u]) {
;                     u32x2 w; w.x = pk2(y[0], y[1]); w.y = pk2(y[2], y[3]); *(u32x2*)(XG + img_off((unsigned)r, (unsigned)k0, 16u)) = w;
;                 }
.LBB0_103:
	s_or_b64 exec, exec, s[42:43]
	v_min_i32_e32 v53, 0x4000, v34
	v_ashrrev_i32_e32 v53, 12, v53
	v_readlane_b32 s8, v251, 0
	v_mul_hi_i32_i24_e32 v55, 0x6000, v53
	v_mul_i32_i24_e32 v54, 0x6000, v53
	v_readlane_b32 s9, v251, 1
	v_readlane_b32 s22, v251, 14
	v_readlane_b32 s23, v251, 15
	s_mov_b64 s[8:9], 0x1000
	v_lshrrev_b32_e32 v75, 3, v34
	v_lshl_add_u64 v[54:55], s[22:23], 0, v[54:55]
	v_lshl_add_u64 v[58:59], v[54:55], 0, s[8:9]
	v_lshl_add_u64 v[54:55], v[58:59], 0, v[206:207]
	global_load_dwordx4 v[54:57], v[54:55], off
	s_nop 0
	global_load_dwordx4 v[76:79], v[40:41], off
	v_lshlrev_b32_e32 v86, 2, v42
	v_mov_b32_e32 v87, v207
	v_lshl_add_u64 v[88:89], v[58:59], 0, v[86:87]
	global_load_dwordx4 v[96:99], v[88:89], off
	global_load_dwordx4 v[108:111], v[40:41], off offset:1024
	v_lshlrev_b32_e32 v86, 2, v44
	v_mov_b32_e32 v87, v207
	v_lshl_add_u64 v[90:91], v[58:59], 0, v[86:87]
	global_load_dwordx4 v[100:103], v[90:91], off
	global_load_dwordx4 v[112:115], v[40:41], off offset:2048
	v_lshlrev_b32_e32 v86, 2, v46
	v_mov_b32_e32 v87, v207
	v_lshl_add_u64 v[92:93], v[58:59], 0, v[86:87]
	global_load_dwordx4 v[104:107], v[92:93], off
	global_load_dwordx4 v[116:119], v[40:41], off offset:3072
	v_lshlrev_b32_e32 v80, 5, v34
	v_lshlrev_b32_e32 v82, 1, v34
	s_mov_b32 s28, 0x3fff00
	v_and_or_b32 v75, v75, 14, v62
	v_and_b32_e32 v80, 0x1e0, v80
	v_and_b32_e32 v82, 16, v82
	v_and_b32_e32 v53, 0x2000, v72
	v_and_or_b32 v83, v34, s28, v43
	v_lshlrev_b32_e32 v75, 9, v75
	v_bitop3_b32 v80, v80, v82, v63 bitop3:0x36
	v_lshlrev_b32_e32 v83, 10, v83
	v_or3_b32 v75, v80, v75, v53
	s_mov_b32 s28, 0xfffcc000
	v_and_or_b32 v80, v83, s28, v75
	s_brev_b32 s28, -2
	v_mov_b32_e32 v81, v207
	v_readlane_b32 s10, v251, 2
	v_readlane_b32 s11, v251, 3
	v_readlane_b32 s12, v251, 4
	v_readlane_b32 s13, v251, 5
	v_readlane_b32 s14, v251, 6
	v_readlane_b32 s15, v251, 7
	v_readlane_b32 s16, v251, 8
	v_readlane_b32 s17, v251, 9
	v_readlane_b32 s18, v251, 10
	v_readlane_b32 s19, v251, 11
	v_readlane_b32 s20, v251, 12
	v_readlane_b32 s21, v251, 13
	s_waitcnt vmcnt(0)
	v_pk_add_f32 v[56:57], v[56:57], 1.0 op_sel_hi:[1,0]
	v_pk_add_f32 v[54:55], v[54:55], 1.0 op_sel_hi:[1,0]
	s_waitcnt vmcnt(0)
	v_pk_mul_f32 v[56:57], v[78:79], v[56:57]
	v_pk_mul_f32 v[54:55], v[76:77], v[54:55]
	v_bfi_b32 v77, s28, v235, v56
	v_bfi_b32 v53, s28, v235, v54
	v_bfi_b32 v76, s28, v235, v55
	v_bfi_b32 v78, s28, v235, v57
	s_mov_b32 s28, 0x3727c5ac
	v_cmp_lt_f32_e64 s[42:43], |v55|, s28
	s_nop 1
	v_cndmask_b32_e64 v55, v55, v76, s[42:43]
	v_cmp_lt_f32_e64 s[42:43], |v54|, s28
	s_nop 1
	v_cndmask_b32_e64 v54, v54, v53, s[42:43]
	v_cmp_lt_f32_e64 s[42:43], |v57|, s28
	v_pk_mul_f32 v[54:55], v[30:31], v[54:55]
	s_nop 0
	v_cndmask_b32_e64 v57, v57, v78, s[42:43]
	v_cmp_lt_f32_e64 s[42:43], |v56|, s28
	v_bfe_u32 v53, v54, 16, 1
	v_bfe_u32 v76, v55, 16, 1
	v_cndmask_b32_e64 v56, v56, v77, s[42:43]
	v_pk_mul_f32 v[56:57], v[32:33], v[56:57]
	v_add3_u32 v53, v54, v53, s27
	v_bfe_u32 v77, v56, 16, 1
	v_bfe_u32 v78, v57, 16, 1
	v_add3_u32 v54, v55, v76, s27
	v_add3_u32 v55, v56, v77, s27
	v_add3_u32 v56, v57, v78, s27
	v_lshrrev_b32_e32 v53, 16, v53
	v_lshrrev_b32_e32 v55, 16, v55
	v_and_or_b32 v54, v54, s6, v53
	v_and_or_b32 v55, v56, s6, v55
	v_lshl_add_u64 v[56:57], v[80:81], 1, s[92:93]
	global_store_dwordx2 v[56:57], v[54:55], off
	s_and_saveexec_b64 s[42:43], s[0:1]
	s_cbranch_execz .LBB0_105
	v_mul_f32_e32 v53, v45, v52
	v_mul_f32_e32 v53, 0.15915494, v53
	v_cos_f32_e32 v54, v53
	v_mul_f32_e32 v53, v47, v52
	v_mul_f32_e32 v55, v60, v52
	v_mul_f32_e32 v52, v61, v52
	v_mul_f32_e32 v53, 0.15915494, v53
	v_mul_f32_e32 v55, 0.15915494, v55
	v_mul_f32_e32 v52, 0.15915494, v52
	v_cos_f32_e32 v56, v55
	v_cos_f32_e32 v57, v52
	v_cos_f32_e32 v55, v53
	v_pk_add_f32 v[28:29], v[28:29], v[56:57]
	v_pk_add_f32 v[26:27], v[26:27], v[54:55]
.LBB0_105:
	s_or_b64 exec, exec, s[42:43]
	v_lshlrev_b32_e32 v54, 2, v42
	v_mov_b32_e32 v55, v207
	v_lshl_add_u64 v[52:53], v[58:59], 0, v[54:55]
	s_nop 0
	s_nop 0
	s_brev_b32 s28, -2
	v_lshrrev_b32_e32 v52, 4, v34
	v_and_b32_e32 v55, 0x3fff0, v52
	v_or_b32_e32 v52, v55, v37
	v_mov_b32_e32 v53, v207
	v_lshl_or_b32 v52, v52, 14, v75
	v_and_b32_e32 v84, 63, v34
	v_lshl_add_u64 v[52:53], v[52:53], 1, s[92:93]
	s_nop 0
	v_pk_add_f32 v[56:57], v[98:99], 1.0 op_sel_hi:[1,0]
	v_pk_add_f32 v[76:77], v[96:97], 1.0 op_sel_hi:[1,0]
	s_nop 0
	v_pk_mul_f32 v[56:57], v[110:111], v[56:57]
	v_pk_mul_f32 v[76:77], v[108:109], v[76:77]
	v_bfi_b32 v80, s28, v235, v56
	v_bfi_b32 v78, s28, v235, v76
	v_bfi_b32 v79, s28, v235, v77
	v_bfi_b32 v81, s28, v235, v57
	s_mov_b32 s28, 0x3727c5ac
	v_cmp_lt_f32_e64 s[42:43], |v77|, s28
	s_nop 1
	v_cndmask_b32_e64 v77, v77, v79, s[42:43]
	v_cmp_lt_f32_e64 s[42:43], |v76|, s28
	s_nop 1
	v_cndmask_b32_e64 v76, v76, v78, s[42:43]
	v_cmp_lt_f32_e64 s[42:43], |v57|, s28
	v_pk_mul_f32 v[76:77], v[26:27], v[76:77]
	s_nop 0
	v_cndmask_b32_e64 v57, v57, v81, s[42:43]
	v_cmp_lt_f32_e64 s[42:43], |v56|, s28
	v_bfe_u32 v78, v76, 16, 1
	v_bfe_u32 v79, v77, 16, 1
	v_cndmask_b32_e64 v56, v56, v80, s[42:43]
	v_pk_mul_f32 v[56:57], v[28:29], v[56:57]
	v_add3_u32 v76, v76, v78, s27
	v_bfe_u32 v80, v56, 16, 1
	v_bfe_u32 v81, v57, 16, 1
	v_add3_u32 v56, v56, v80, s27
	v_add3_u32 v77, v77, v79, s27
	v_add3_u32 v57, v57, v81, s27
	v_lshrrev_b32_e32 v76, 16, v76
	v_lshrrev_b32_e32 v78, 16, v56
	v_and_or_b32 v56, v77, s6, v76
	v_and_or_b32 v57, v57, s6, v78
	global_store_dwordx2 v[52:53], v[56:57], off
	v_cvt_f32_ubyte0_e32 v56, v84
	s_and_saveexec_b64 s[42:43], s[0:1]
	s_cbranch_execz .LBB0_107
	v_mul_f32_e32 v57, v60, v56
	v_mul_f32_e32 v57, 0.15915494, v57
	v_mul_f32_e32 v52, v45, v56
	v_mul_f32_e32 v53, v47, v56
	v_sin_f32_e32 v76, v57
	v_mul_f32_e32 v57, v61, v56
	v_mul_f32_e32 v52, 0.15915494, v52
	v_mul_f32_e32 v53, 0.15915494, v53
	v_mul_f32_e32 v57, 0.15915494, v57
	v_sin_f32_e32 v52, v52
	v_sin_f32_e32 v77, v57
	v_sin_f32_e32 v53, v53
	v_pk_add_f32 v[24:25], v[24:25], v[76:77]
	v_pk_add_f32 v[22:23], v[22:23], v[52:53]
; __device__ __forceinline__ unsigned pk2(float lo, float hi) { return f2bf(lo) | (f2bf(hi) << 16); }
; __host__ __device__ __forceinline__ unsigned img_off(unsigned row, unsigned col, unsigned KT) { return (((row >> 8) * KT + (col >> 6)) << 14) + (((row >> 7) & 1u) << 13) + hl_off(row & 127u, col & 63u); }
; __device__ __forceinline__ float gain_clamp(float g) { return fabsf(g) < 1e-5f ? copysignf(1e-5f, g) : g; }
; __device__ __forceinline__ void phase_p0b(const Args& a) {
;     ...
;             for (int j = 0; j < 4; ++j) {
;                 const int k0 = 256 * j + 4 * lane;
;                 f32x4 vv = v[u][j];
;                 if (lat) {
; #pragma unroll
;                     for (int e = 0; e < 4; ++e) { const float ang = ((j < 2) ? prow : pcol) * omega[e]; vv[e] += (j & 1) ? __cosf(ang) : __sinf(ang); }
;                 }
;                 q += (vv[0] * vv[0] + vv[1] * vv[1]) + (vv[2] * vv[2] + vv[3] * vv[3]);
;                 const f32x4 gg = *(const f32x4*)(g1 + k0);
;                 const f32x4 sc = *(const f32x4*)(mod + (size_t)bb * NMODC + DM + k0);
;                 f32x4 gc = gg * (1.0f + sc);
; #pragma unroll
;                 for (int e = 0; e < 4; ++e) gc[e] = gain_clamp(gc[e]);
;                 const f32x4 y = vv * gc;
;                 if (okr[u]) {
;                     u32x2 w; w.x = pk2(y[0], y[1]); w.y = pk2(y[2], y[3]); *(u32x2*)(XG + img_off((unsigned)r, (unsigned)k0, 16u)) = w;
;                 }
;             }
;             q = wave_sum(q);
;             if (lane < 16 && okr[u]) ss[(size_t)r * 16 + lane] = lane == 0 ? q : 0.f;
.LBB0_107:
	s_or_b64 exec, exec, s[42:43]
	v_lshlrev_b32_e32 v52, 2, v44
	v_mov_b32_e32 v53, v207
	v_lshl_add_u64 v[76:77], v[58:59], 0, v[52:53]
	s_nop 0
	s_nop 0
	s_nop 0
	v_or_b32_e32 v53, v55, v70
	s_brev_b32 s28, -2
	v_lshl_or_b32 v84, v53, 14, v75
	v_mov_b32_e32 v85, v207
	s_nop 0
	v_pk_add_f32 v[78:79], v[102:103], 1.0 op_sel_hi:[1,0]
	v_pk_add_f32 v[76:77], v[100:101], 1.0 op_sel_hi:[1,0]
	s_nop 0
	v_pk_mul_f32 v[78:79], v[114:115], v[78:79]
	v_pk_mul_f32 v[76:77], v[112:113], v[76:77]
	v_bfi_b32 v80, s28, v235, v78
	v_bfi_b32 v53, s28, v235, v76
	v_bfi_b32 v57, s28, v235, v77
	v_bfi_b32 v81, s28, v235, v79
	s_mov_b32 s28, 0x3727c5ac
	v_cmp_lt_f32_e64 s[42:43], |v77|, s28
	s_nop 1
	v_cndmask_b32_e64 v77, v77, v57, s[42:43]
	v_cmp_lt_f32_e64 s[42:43], |v76|, s28
	s_nop 1
	v_cndmask_b32_e64 v76, v76, v53, s[42:43]
	v_cmp_lt_f32_e64 s[42:43], |v79|, s28
	v_pk_mul_f32 v[76:77], v[22:23], v[76:77]
	s_nop 0
	v_cndmask_b32_e64 v79, v79, v81, s[42:43]
	v_cmp_lt_f32_e64 s[42:43], |v78|, s28
	v_bfe_u32 v53, v76, 16, 1
	v_bfe_u32 v57, v77, 16, 1
	v_cndmask_b32_e64 v78, v78, v80, s[42:43]
	v_pk_mul_f32 v[78:79], v[24:25], v[78:79]
	v_add3_u32 v53, v76, v53, s27
	v_bfe_u32 v80, v78, 16, 1
	v_bfe_u32 v81, v79, 16, 1
	v_add3_u32 v76, v78, v80, s27
	v_add3_u32 v57, v77, v57, s27
	v_add3_u32 v77, v79, v81, s27
	v_lshrrev_b32_e32 v53, 16, v53
	v_lshrrev_b32_e32 v78, 16, v76
	v_and_or_b32 v76, v57, s6, v53
	v_and_or_b32 v77, v77, s6, v78
	v_lshl_add_u64 v[78:79], v[84:85], 1, s[92:93]
	global_store_dwordx2 v[78:79], v[76:77], off
	s_and_saveexec_b64 s[42:43], s[0:1]
	s_cbranch_execz .LBB0_109
	v_mul_f32_e32 v53, v45, v56
	v_mul_f32_e32 v53, 0.15915494, v53
	v_cos_f32_e32 v76, v53
	v_mul_f32_e32 v53, v47, v56
	v_mul_f32_e32 v57, v60, v56
	v_mul_f32_e32 v56, v61, v56
	v_mul_f32_e32 v53, 0.15915494, v53
	v_mul_f32_e32 v57, 0.15915494, v57
	v_mul_f32_e32 v56, 0.15915494, v56
	v_cos_f32_e32 v78, v57
	v_cos_f32_e32 v79, v56
	v_cos_f32_e32 v77, v53
	v_pk_add_f32 v[20:21], v[78:79], v[20:21]
	v_pk_add_f32 v[18:19], v[76:77], v[18:19]
.LBB0_109:
	s_or_b64 exec, exec, s[42:43]
	v_lshlrev_b32_e32 v56, 2, v46
	v_mov_b32_e32 v57, v207
	v_lshl_add_u64 v[58:59], v[58:59], 0, v[56:57]
	s_nop 0
	s_nop 0
	v_mul_f32_e32 v31, v31, v31
	v_mul_f32_e32 v33, v33, v33
	v_mul_f32_e32 v27, v27, v27
	v_mul_f32_e32 v29, v29, v29
	v_mul_f32_e32 v23, v23, v23
	v_mul_f32_e32 v25, v25, v25
	v_fmac_f32_e32 v31, v30, v30
	v_fmac_f32_e32 v33, v32, v32
	v_fmac_f32_e32 v27, v26, v26
	v_fmac_f32_e32 v29, v28, v28
	v_mul_f32_e32 v53, v19, v19
	v_mul_f32_e32 v57, v21, v21
	v_fmac_f32_e32 v23, v22, v22
	v_fmac_f32_e32 v25, v24, v24
	v_add_f32_e32 v22, v31, v33
	v_add_f32_e32 v24, v27, v29
	v_fmac_f32_e32 v53, v18, v18
	v_fmac_f32_e32 v57, v20, v20
	v_add_f32_e32 v23, v23, v25
	v_add_f32_e32 v22, v22, v24
	v_add_f32_e32 v25, v53, v57
	v_add_f32_e32 v22, v22, v23
	v_add_f32_e32 v22, v22, v25
	ds_bpermute_b32 v23, v64, v22
	s_brev_b32 s0, -2
	v_or_b32_e32 v24, v55, v71
	v_mov_b32_e32 v25, v207
	v_lshl_or_b32 v24, v24, 14, v75
	s_waitcnt lgkmcnt(0)
	v_add_f32_e32 v22, v22, v23
	ds_bpermute_b32 v23, v65, v22
	s_waitcnt lgkmcnt(0)
	v_add_f32_e32 v22, v22, v23
	ds_bpermute_b32 v23, v66, v22
	s_waitcnt lgkmcnt(0)
	v_add_f32_e32 v22, v22, v23
	ds_bpermute_b32 v23, v67, v22
	s_waitcnt lgkmcnt(0)
	v_add_f32_e32 v22, v22, v23
	ds_bpermute_b32 v23, v68, v22
	s_waitcnt lgkmcnt(0)
	v_add_f32_e32 v22, v22, v23
	ds_bpermute_b32 v23, v69, v22
	s_nop 0
	v_pk_add_f32 v[26:27], v[106:107], 1.0 op_sel_hi:[1,0]
	v_pk_add_f32 v[28:29], v[104:105], 1.0 op_sel_hi:[1,0]
	s_nop 0
	v_pk_mul_f32 v[26:27], v[118:119], v[26:27]
	v_pk_mul_f32 v[28:29], v[116:117], v[28:29]
	v_bfi_b32 v32, s0, v235, v26
	v_bfi_b32 v30, s0, v235, v28
	v_bfi_b32 v31, s0, v235, v29
	v_bfi_b32 v33, s0, v235, v27
	v_cmp_lt_f32_e64 s[0:1], |v29|, s28
	s_nop 1
	v_cndmask_b32_e64 v29, v29, v31, s[0:1]
	v_cmp_lt_f32_e64 s[0:1], |v28|, s28
	s_nop 1
	v_cndmask_b32_e64 v28, v28, v30, s[0:1]
	v_cmp_lt_f32_e64 s[0:1], |v27|, s28
	v_pk_mul_f32 v[18:19], v[18:19], v[28:29]
	s_nop 0
	v_cndmask_b32_e64 v27, v27, v33, s[0:1]
	v_cmp_lt_f32_e64 s[0:1], |v26|, s28
	s_nop 1
	v_cndmask_b32_e64 v26, v26, v32, s[0:1]
	v_pk_mul_f32 v[20:21], v[20:21], v[26:27]
	v_bfe_u32 v26, v18, 16, 1
	v_bfe_u32 v28, v20, 16, 1
	v_bfe_u32 v27, v19, 16, 1
	v_bfe_u32 v29, v21, 16, 1
	v_add3_u32 v18, v18, v26, s27
	v_add3_u32 v20, v20, v28, s27
	v_add3_u32 v19, v19, v27, s27
	v_add3_u32 v21, v21, v29, s27
	v_lshrrev_b32_e32 v18, 16, v18
	v_lshrrev_b32_e32 v20, 16, v20
	v_and_or_b32 v18, v19, s6, v18
	v_and_or_b32 v19, v21, s6, v20
	v_lshl_add_u64 v[20:21], v[24:25], 1, s[92:93]
	global_store_dwordx2 v[20:21], v[18:19], off
	s_and_saveexec_b64 s[0:1], vcc
	s_cbranch_execz .LBB0_111
	s_waitcnt lgkmcnt(0)
	v_add_f32_e32 v18, v22, v23
	v_cndmask_b32_e64 v20, 0, v18, s[36:37]
	v_lshl_add_u64 v[18:19], v[38:39], 0, v[50:51]
	global_store_dword v[18:19], v20, off
